# gemm256 early-wave K-loops: first six LDS fragment reads issued right behind the barrier, before the global prefetch block
# speedup vs baseline: 1.0039x; 1.0039x over previous
; template <bool TR>
; DI void gemm256_compute(f32x16 (&acc)[4][2], const unsigned char* As, const unsigned char* Bs) {
;   __builtin_amdgcn_s_setprio(2);
;   bf16x8 b0 = *(const bf16x8*)(Bs), b1 = *(const bf16x8*)(Bs + 32 * G_AST);
;   bf16x8 a0 = *(const bf16x8*)(As), a1 = *(const bf16x8*)(As + 32 * G_AST), a2 = *(const bf16x8*)(As + 64 * G_AST), a3 = *(const bf16x8*)(As + 96 * G_AST);
; #pragma unroll
;   for (int ks = 0; ks < 4; ++ks) {
;     bf16x8 nb0 = b0, nb1 = b1, na0 = a0, na1 = a1, na2 = a2, na3 = a3;
;     if (ks < 3) {
;       nb0 = *(const bf16x8*)(Bs + (ks + 1) * 32); nb1 = *(const bf16x8*)(Bs + 32 * G_AST + (ks + 1) * 32);
;       na0 = *(const bf16x8*)(As + (ks + 1) * 32); na1 = *(const bf16x8*)(As + 32 * G_AST + (ks + 1) * 32);
;       na2 = *(const bf16x8*)(As + 64 * G_AST + (ks + 1) * 32); na3 = *(const bf16x8*)(As + 96 * G_AST + (ks + 1) * 32);
;     }
;     if (TR) {
;       acc[0][0] = MFMA16(b0, a0, acc[0][0]); acc[0][1] = MFMA16(b1, a0, acc[0][1]);
;       acc[1][0] = MFMA16(b0, a1, acc[1][0]); acc[1][1] = MFMA16(b1, a1, acc[1][1]);
;       acc[2][0] = MFMA16(b0, a2, acc[2][0]); acc[2][1] = MFMA16(b1, a2, acc[2][1]);
;       acc[3][0] = MFMA16(b0, a3, acc[3][0]); acc[3][1] = MFMA16(b1, a3, acc[3][1]);
;     } else {
;       acc[0][0] = MFMA16(a0, b0, acc[0][0]); acc[0][1] = MFMA16(a0, b1, acc[0][1]);
;       acc[1][0] = MFMA16(a1, b0, acc[1][0]); acc[1][1] = MFMA16(a1, b1, acc[1][1]);
;       acc[2][0] = MFMA16(a2, b0, acc[2][0]); acc[2][1] = MFMA16(a2, b1, acc[2][1]);
;       acc[3][0] = MFMA16(a3, b0, acc[3][0]); acc[3][1] = MFMA16(a3, b1, acc[3][1]);
;     }
;     if (ks < 3) {
;       __builtin_amdgcn_sched_group_barrier(0x100, 6, 0);
;       __builtin_amdgcn_sched_group_barrier(0x008, 8, 0);
;     }
;     b0 = nb0; b1 = nb1; a0 = na0; a1 = na1; a2 = na2; a3 = na3;
;   }
; template <bool TR = false>
; DI void gemm256(f32x16 (&acc)[4][2], const u16* const (&ap)[4], const u16* b0p, int K, unsigned char* lds) {
;     ...
;   if (!late) {
;     for (int kt = 0; kt < nk; ++kt) {
;       const bool more = kt + 1 < nk;
;       if (more) G2_LOADR(kt + 1);
;       __builtin_amdgcn_sched_barrier(0);
;       gemm256_compute<TR>(acc, As0 + (kt & 1) * G2_STAGE, Bs0 + (kt & 1) * G2_STAGE);
;       __builtin_amdgcn_sched_barrier(0);
;       if (more) G2_STORER(lds + ((kt + 1) & 1) * G2_STAGE);
;       __syncthreads();
;     }
.LBB0_215:
	s_bitcmp1_b32 s5, 0
	s_cselect_b32 s32, 0x12000, 0
	v_add_u32_e32 v210, s32, v1
	v_add_u32_e32 v211, s32, v184
	ds_read_b128 v[186:189], v210 offset:4608
	ds_read_b128 v[198:201], v210 offset:9216
	ds_read_b128 v[202:205], v210 offset:13824
	ds_read_b128 v[190:193], v211 offset:36864
	ds_read_b128 v[194:197], v211 offset:41472
	ds_read_b128 v[206:209], v211 offset:36896
	s_waitcnt vmcnt(5)
	v_lshl_add_u64 v[138:139], v[182:183], 0, s[12:13]
	v_add_co_u32_e32 v130, vcc, s48, v138
	s_waitcnt vmcnt(1)
	v_lshl_add_u64 v[154:155], v[162:163], 0, s[12:13]
	v_addc_co_u32_e32 v131, vcc, 0, v139, vcc
	v_add_co_u32_e32 v134, vcc, s49, v138
	global_load_dwordx4 v[130:133], v[130:131], off
	s_nop 0
	v_addc_co_u32_e32 v135, vcc, 0, v139, vcc
	v_add_co_u32_e32 v140, vcc, s58, v138
	global_load_dwordx4 v[134:137], v[134:135], off
	s_nop 0
	v_addc_co_u32_e32 v141, vcc, 0, v139, vcc
	v_add_co_u32_e32 v142, vcc, s59, v138
	s_add_i32 s11, s5, 1
	s_nop 0
	v_addc_co_u32_e32 v143, vcc, 0, v139, vcc
	v_add_co_u32_e32 v146, vcc, s2, v154
	global_load_dwordx4 v[138:141], v[140:141], off
	s_nop 0
	v_addc_co_u32_e32 v147, vcc, 0, v155, vcc
	v_add_co_u32_e32 v150, vcc, s3, v154
	global_load_dwordx4 v[142:145], v[142:143], off
	s_nop 0
	v_addc_co_u32_e32 v151, vcc, 0, v155, vcc
	v_add_co_u32_e32 v156, vcc, s80, v154
	global_load_dwordx4 v[146:149], v[146:147], off
	s_nop 0
	v_addc_co_u32_e32 v157, vcc, 0, v155, vcc
	s_waitcnt vmcnt(5)
	v_add_co_u32_e32 v158, vcc, s81, v154
	global_load_dwordx4 v[150:153], v[150:151], off
	s_nop 0
	v_addc_co_u32_e32 v159, vcc, 0, v155, vcc
	global_load_dwordx4 v[154:157], v[156:157], off
	s_nop 0
	global_load_dwordx4 v[158:161], v[158:159], off
	s_bitcmp1_b32 s5, 0
	s_cselect_b32 s5, 0x12000, 0
	s_setprio 2
	s_waitcnt lgkmcnt(2)
	v_mfma_f32_32x32x16_bf16 v[34:49], v[186:189], v[190:193], v[34:49]
	s_waitcnt lgkmcnt(1)
	v_mfma_f32_32x32x16_bf16 v[50:65], v[186:189], v[194:197], v[50:65]
	v_mfma_f32_32x32x16_bf16 v[66:81], v[198:201], v[190:193], v[66:81]
	v_mfma_f32_32x32x16_bf16 v[82:97], v[198:201], v[194:197], v[82:97]
	v_mfma_f32_32x32x16_bf16 v[98:113], v[202:205], v[190:193], v[98:113]
	v_mfma_f32_32x32x16_bf16 v[114:129], v[202:205], v[194:197], v[114:129]
	ds_read_b128 v[186:189], v210
	ds_read_b128 v[232:235], v210 offset:9248
	ds_read_b128 v[236:239], v210 offset:13856
	ds_read_b128 v[198:201], v211 offset:41504
	s_waitcnt lgkmcnt(3)
	v_mfma_f32_32x32x16_bf16 v[2:17], v[186:189], v[190:193], v[2:17]
	s_waitcnt lgkmcnt(2)
	v_mfma_f32_32x32x16_bf16 v[66:81], v[232:235], v[206:209], v[66:81]
	s_waitcnt lgkmcnt(0)
	v_mfma_f32_32x32x16_bf16 v[82:97], v[232:235], v[198:201], v[82:97]
	ds_read_b128 v[232:235], v210 offset:13888
	ds_read_b128 v[190:193], v211 offset:41536
	v_mfma_f32_32x32x16_bf16 v[114:129], v[236:239], v[198:201], v[114:129]
	s_waitcnt lgkmcnt(0)
	v_mfma_f32_32x32x16_bf16 v[114:129], v[232:235], v[190:193], v[114:129]
	v_mfma_f32_32x32x16_bf16 v[18:33], v[186:189], v[194:197], v[18:33]
	ds_read_b128 v[186:189], v211 offset:36928
	v_mfma_f32_32x32x16_bf16 v[98:113], v[236:239], v[206:209], v[98:113]
	s_waitcnt lgkmcnt(0)
	v_mfma_f32_32x32x16_bf16 v[98:113], v[232:235], v[186:189], v[98:113]
	ds_read_b128 v[202:205], v210 offset:32
	ds_read_b128 v[226:229], v210 offset:4640
	s_waitcnt lgkmcnt(1)
	v_mfma_f32_32x32x16_bf16 v[2:17], v[202:205], v[206:209], v[2:17]
	v_mfma_f32_32x32x16_bf16 v[18:33], v[202:205], v[198:201], v[18:33]
	s_waitcnt lgkmcnt(0)
	v_mfma_f32_32x32x16_bf16 v[34:49], v[226:229], v[206:209], v[34:49]
	v_mfma_f32_32x32x16_bf16 v[50:65], v[226:229], v[198:201], v[50:65]
	ds_read_b128 v[194:197], v210 offset:64
	ds_read_b128 v[202:205], v210 offset:4672
	ds_read_b128 v[226:229], v210 offset:9280
	s_waitcnt lgkmcnt(2)
	v_mfma_f32_32x32x16_bf16 v[2:17], v[194:197], v[186:189], v[2:17]
	s_waitcnt lgkmcnt(1)
	v_mfma_f32_32x32x16_bf16 v[34:49], v[202:205], v[186:189], v[34:49]
	s_waitcnt lgkmcnt(0)
	v_mfma_f32_32x32x16_bf16 v[66:81], v[226:229], v[186:189], v[66:81]
	ds_read_b128 v[186:189], v210 offset:96
	v_mfma_f32_32x32x16_bf16 v[18:33], v[194:197], v[190:193], v[18:33]
	ds_read_b128 v[194:197], v211 offset:41568
	v_mfma_f32_32x32x16_bf16 v[50:65], v[202:205], v[190:193], v[50:65]
	v_mfma_f32_32x32x16_bf16 v[82:97], v[226:229], v[190:193], v[82:97]
	ds_read_b128 v[190:193], v211 offset:36960
	s_waitcnt lgkmcnt(0)
	v_mfma_f32_32x32x16_bf16 v[2:17], v[186:189], v[190:193], v[2:17]
	v_mfma_f32_32x32x16_bf16 v[18:33], v[186:189], v[194:197], v[18:33]
	ds_read_b128 v[186:189], v210 offset:4704
	s_waitcnt lgkmcnt(0)
	v_mfma_f32_32x32x16_bf16 v[34:49], v[186:189], v[190:193], v[34:49]
	v_mfma_f32_32x32x16_bf16 v[50:65], v[186:189], v[194:197], v[50:65]
	ds_read_b128 v[186:189], v210 offset:9312
	s_waitcnt lgkmcnt(0)
	v_mfma_f32_32x32x16_bf16 v[66:81], v[186:189], v[190:193], v[66:81]
	v_mfma_f32_32x32x16_bf16 v[82:97], v[186:189], v[194:197], v[82:97]
	ds_read_b128 v[186:189], v210 offset:13920
	s_waitcnt lgkmcnt(0)
	v_mfma_f32_32x32x16_bf16 v[98:113], v[186:189], v[190:193], v[98:113]
	v_mfma_f32_32x32x16_bf16 v[114:129], v[186:189], v[194:197], v[114:129]
	s_setprio 0
	s_bitcmp1_b32 s11, 0
	s_cselect_b32 s5, 0x12000, 0
	s_add_u32 s12, s12, 0x8000
	s_addc_u32 s13, s13, 0
	v_add_u32_e32 v186, s5, v185
	s_cmp_eq_u32 s12, 0x78000
	s_mov_b32 s5, s11
	s_waitcnt vmcnt(7)
	ds_write_b128 v186, v[130:133]
	s_waitcnt vmcnt(6)
	ds_write_b128 v186, v[134:137] offset:9216
	s_waitcnt vmcnt(5)
	ds_write_b128 v186, v[138:141] offset:18432
	s_waitcnt vmcnt(4)
	ds_write_b128 v186, v[142:145] offset:27648
	s_waitcnt vmcnt(3)
	ds_write_b128 v186, v[146:149] offset:36864
	s_waitcnt vmcnt(2)
	ds_write_b128 v186, v[150:153] offset:46080
	s_waitcnt vmcnt(1)
	ds_write_b128 v186, v[154:157] offset:55296
	s_waitcnt vmcnt(0)
	ds_write_b128 v186, v[158:161] offset:64512
	s_waitcnt lgkmcnt(0)
	s_barrier
; template <bool TR>
; DI void gemm256_compute(f32x16 (&acc)[4][2], const unsigned char* As, const unsigned char* Bs) {
;   __builtin_amdgcn_s_setprio(2);
;   bf16x8 b0 = *(const bf16x8*)(Bs), b1 = *(const bf16x8*)(Bs + 32 * G_AST);
;   bf16x8 a0 = *(const bf16x8*)(As), a1 = *(const bf16x8*)(As + 32 * G_AST), a2 = *(const bf16x8*)(As + 64 * G_AST), a3 = *(const bf16x8*)(As + 96 * G_AST);
; #pragma unroll
;   for (int ks = 0; ks < 4; ++ks) {
;     bf16x8 nb0 = b0, nb1 = b1, na0 = a0, na1 = a1, na2 = a2, na3 = a3;
;     if (ks < 3) {
;       nb0 = *(const bf16x8*)(Bs + (ks + 1) * 32); nb1 = *(const bf16x8*)(Bs + 32 * G_AST + (ks + 1) * 32);
;       na0 = *(const bf16x8*)(As + (ks + 1) * 32); na1 = *(const bf16x8*)(As + 32 * G_AST + (ks + 1) * 32);
;       na2 = *(const bf16x8*)(As + 64 * G_AST + (ks + 1) * 32); na3 = *(const bf16x8*)(As + 96 * G_AST + (ks + 1) * 32);
;     }
;     if (TR) {
;       acc[0][0] = MFMA16(b0, a0, acc[0][0]); acc[0][1] = MFMA16(b1, a0, acc[0][1]);
;       acc[1][0] = MFMA16(b0, a1, acc[1][0]); acc[1][1] = MFMA16(b1, a1, acc[1][1]);
;       acc[2][0] = MFMA16(b0, a2, acc[2][0]); acc[2][1] = MFMA16(b1, a2, acc[2][1]);
;       acc[3][0] = MFMA16(b0, a3, acc[3][0]); acc[3][1] = MFMA16(b1, a3, acc[3][1]);
;     } else {
;       acc[0][0] = MFMA16(a0, b0, acc[0][0]); acc[0][1] = MFMA16(a0, b1, acc[0][1]);
;       acc[1][0] = MFMA16(a1, b0, acc[1][0]); acc[1][1] = MFMA16(a1, b1, acc[1][1]);
;       acc[2][0] = MFMA16(a2, b0, acc[2][0]); acc[2][1] = MFMA16(a2, b1, acc[2][1]);
;       acc[3][0] = MFMA16(a3, b0, acc[3][0]); acc[3][1] = MFMA16(a3, b1, acc[3][1]);
;     }
;     if (ks < 3) {
;       __builtin_amdgcn_sched_group_barrier(0x100, 6, 0);
;       __builtin_amdgcn_sched_group_barrier(0x008, 8, 0);
;     }
;     b0 = nb0; b1 = nb1; a0 = na0; a1 = na1; a2 = na2; a3 = na3;
;   }
; template <bool TR = false>
; DI void gemm256(f32x16 (&acc)[4][2], const u16* const (&ap)[4], const u16* b0p, int K, unsigned char* lds) {
;     ...
;   if (!late) {
;     for (int kt = 0; kt < nk; ++kt) {
;       const bool more = kt + 1 < nk;
;       if (more) G2_LOADR(kt + 1);
;       __builtin_amdgcn_sched_barrier(0);
;       gemm256_compute<TR>(acc, As0 + (kt & 1) * G2_STAGE, Bs0 + (kt & 1) * G2_STAGE);
;       __builtin_amdgcn_sched_barrier(0);
;       if (more) G2_STORER(lds + ((kt + 1) & 1) * G2_STAGE);
;       __syncthreads();
;     }
	s_cbranch_scc0 .LBB0_215
	v_add_u32_e32 v134, 0x12000, v1
	v_add_u32_e32 v130, 0x12000, v178
	s_setprio 2
	v_add_u32_e32 v142, 0x13200, v1
	v_add_u32_e32 v146, 0x14400, v1
	v_add_u32_e32 v150, 0x15600, v1
	ds_read_b128 v[134:137], v134
	ds_read_b128 v[142:145], v142
	ds_read_b128 v[146:149], v146
	ds_read_b128 v[150:153], v150
	v_add_u32_e32 v138, 0x13200, v178
	ds_read_b128 v[130:133], v130
	ds_read_b128 v[138:141], v138
	s_waitcnt lgkmcnt(1)
	v_mfma_f32_32x32x16_bf16 v[2:17], v[134:137], v[130:133], v[2:17]
	s_waitcnt lgkmcnt(0)
	v_mfma_f32_32x32x16_bf16 v[18:33], v[134:137], v[138:141], v[18:33]
	v_add_u32_e32 v134, 0x12020, v1
	v_mfma_f32_32x32x16_bf16 v[34:49], v[142:145], v[130:133], v[34:49]
	v_mfma_f32_32x32x16_bf16 v[50:65], v[142:145], v[138:141], v[50:65]
	v_add_u32_e32 v142, 0x13220, v1
	v_mfma_f32_32x32x16_bf16 v[66:81], v[146:149], v[130:133], v[66:81]
	v_mfma_f32_32x32x16_bf16 v[82:97], v[146:149], v[138:141], v[82:97]
	v_add_u32_e32 v146, 0x14420, v1
	v_mfma_f32_32x32x16_bf16 v[98:113], v[150:153], v[130:133], v[98:113]
	v_add_u32_e32 v130, 0x12020, v178
	v_mfma_f32_32x32x16_bf16 v[114:129], v[150:153], v[138:141], v[114:129]
	v_add_u32_e32 v150, 0x15620, v1
	ds_read_b128 v[134:137], v134
	ds_read_b128 v[142:145], v142
	ds_read_b128 v[146:149], v146
	ds_read_b128 v[150:153], v150
	v_add_u32_e32 v138, 0x13220, v178
	ds_read_b128 v[130:133], v130
	ds_read_b128 v[138:141], v138
	s_waitcnt lgkmcnt(1)
	v_mfma_f32_32x32x16_bf16 v[2:17], v[134:137], v[130:133], v[2:17]
	s_waitcnt lgkmcnt(0)
	v_mfma_f32_32x32x16_bf16 v[18:33], v[134:137], v[138:141], v[18:33]
	v_add_u32_e32 v134, 0x12040, v1
	v_mfma_f32_32x32x16_bf16 v[34:49], v[142:145], v[130:133], v[34:49]
	v_mfma_f32_32x32x16_bf16 v[50:65], v[142:145], v[138:141], v[50:65]
	v_add_u32_e32 v142, 0x13240, v1
	v_mfma_f32_32x32x16_bf16 v[66:81], v[146:149], v[130:133], v[66:81]
	v_mfma_f32_32x32x16_bf16 v[82:97], v[146:149], v[138:141], v[82:97]
	v_add_u32_e32 v146, 0x14440, v1
	v_mfma_f32_32x32x16_bf16 v[98:113], v[150:153], v[130:133], v[98:113]
	v_add_u32_e32 v130, 0x12040, v178
	v_mfma_f32_32x32x16_bf16 v[114:129], v[150:153], v[138:141], v[114:129]
	v_add_u32_e32 v150, 0x15640, v1
	ds_read_b128 v[134:137], v134
	ds_read_b128 v[142:145], v142
	ds_read_b128 v[146:149], v146
	ds_read_b128 v[150:153], v150
	ds_read_b128 v[130:133], v130
	v_add_u32_e32 v138, 0x13240, v178
	ds_read_b128 v[138:141], v138
	s_waitcnt lgkmcnt(1)
	v_mfma_f32_32x32x16_bf16 v[2:17], v[134:137], v[130:133], v[2:17]
	v_mfma_f32_32x32x16_bf16 v[34:49], v[142:145], v[130:133], v[34:49]
	v_mfma_f32_32x32x16_bf16 v[66:81], v[146:149], v[130:133], v[66:81]
	v_mfma_f32_32x32x16_bf16 v[98:113], v[150:153], v[130:133], v[98:113]
	v_add_u32_e32 v130, 0x12060, v1
	ds_read_b128 v[130:133], v130
	s_waitcnt lgkmcnt(1)
	v_mfma_f32_32x32x16_bf16 v[18:33], v[134:137], v[138:141], v[18:33]
	v_add_u32_e32 v134, 0x12060, v178
	ds_read_b128 v[134:137], v134
	v_mfma_f32_32x32x16_bf16 v[50:65], v[142:145], v[138:141], v[50:65]
	v_add_u32_e32 v142, 0x13260, v1
	v_mfma_f32_32x32x16_bf16 v[82:97], v[146:149], v[138:141], v[82:97]
	v_mfma_f32_32x32x16_bf16 v[114:129], v[150:153], v[138:141], v[114:129]
	v_add_u32_e32 v138, 0x13260, v178
	ds_read_b128 v[138:141], v138
	s_waitcnt lgkmcnt(1)
	v_mfma_f32_32x32x16_bf16 v[2:17], v[130:133], v[134:137], v[2:17]
	s_waitcnt lgkmcnt(0)
	v_mfma_f32_32x32x16_bf16 v[18:33], v[130:133], v[138:141], v[18:33]
	ds_read_b128 v[130:133], v142
	v_add_u32_e32 v142, 0x14460, v1
	v_add_u32_e32 v1, 0x15660, v1
	s_waitcnt lgkmcnt(0)
	v_mfma_f32_32x32x16_bf16 v[34:49], v[130:133], v[134:137], v[34:49]
	v_mfma_f32_32x32x16_bf16 v[50:65], v[130:133], v[138:141], v[50:65]
	ds_read_b128 v[130:133], v142
	s_waitcnt lgkmcnt(0)
	v_mfma_f32_32x32x16_bf16 v[66:81], v[130:133], v[134:137], v[66:81]
	v_mfma_f32_32x32x16_bf16 v[82:97], v[130:133], v[138:141], v[82:97]
	ds_read_b128 v[130:133], v1
	s_waitcnt lgkmcnt(0)
	v_mfma_f32_32x32x16_bf16 v[98:113], v[130:133], v[134:137], v[98:113]
	v_mfma_f32_32x32x16_bf16 v[114:129], v[130:133], v[138:141], v[114:129]
	s_setprio 0
	s_barrier

; template <bool TR>
; DI void gemm256_compute(f32x16 (&acc)[4][2], const unsigned char* As, const unsigned char* Bs) {
;   __builtin_amdgcn_s_setprio(2);
;   bf16x8 b0 = *(const bf16x8*)(Bs), b1 = *(const bf16x8*)(Bs + 32 * G_AST);
;   bf16x8 a0 = *(const bf16x8*)(As), a1 = *(const bf16x8*)(As + 32 * G_AST), a2 = *(const bf16x8*)(As + 64 * G_AST), a3 = *(const bf16x8*)(As + 96 * G_AST);
; #pragma unroll
;   for (int ks = 0; ks < 4; ++ks) {
;     bf16x8 nb0 = b0, nb1 = b1, na0 = a0, na1 = a1, na2 = a2, na3 = a3;
;     if (ks < 3) {
;       nb0 = *(const bf16x8*)(Bs + (ks + 1) * 32); nb1 = *(const bf16x8*)(Bs + 32 * G_AST + (ks + 1) * 32);
;       na0 = *(const bf16x8*)(As + (ks + 1) * 32); na1 = *(const bf16x8*)(As + 32 * G_AST + (ks + 1) * 32);
;       na2 = *(const bf16x8*)(As + 64 * G_AST + (ks + 1) * 32); na3 = *(const bf16x8*)(As + 96 * G_AST + (ks + 1) * 32);
;     }
;     if (TR) {
;       acc[0][0] = MFMA16(b0, a0, acc[0][0]); acc[0][1] = MFMA16(b1, a0, acc[0][1]);
;       acc[1][0] = MFMA16(b0, a1, acc[1][0]); acc[1][1] = MFMA16(b1, a1, acc[1][1]);
;       acc[2][0] = MFMA16(b0, a2, acc[2][0]); acc[2][1] = MFMA16(b1, a2, acc[2][1]);
;       acc[3][0] = MFMA16(b0, a3, acc[3][0]); acc[3][1] = MFMA16(b1, a3, acc[3][1]);
;     } else {
;       acc[0][0] = MFMA16(a0, b0, acc[0][0]); acc[0][1] = MFMA16(a0, b1, acc[0][1]);
;       acc[1][0] = MFMA16(a1, b0, acc[1][0]); acc[1][1] = MFMA16(a1, b1, acc[1][1]);
;       acc[2][0] = MFMA16(a2, b0, acc[2][0]); acc[2][1] = MFMA16(a2, b1, acc[2][1]);
;       acc[3][0] = MFMA16(a3, b0, acc[3][0]); acc[3][1] = MFMA16(a3, b1, acc[3][1]);
;     }
;     if (ks < 3) {
;       __builtin_amdgcn_sched_group_barrier(0x100, 6, 0);
;       __builtin_amdgcn_sched_group_barrier(0x008, 8, 0);
;     }
;     b0 = nb0; b1 = nb1; a0 = na0; a1 = na1; a2 = na2; a3 = na3;
;   }
; template <bool TR = false>
; DI void gemm256(f32x16 (&acc)[4][2], const u16* const (&ap)[4], const u16* b0p, int K, unsigned char* lds) {
;     ...
;   if (!late) {
;     for (int kt = 0; kt < nk; ++kt) {
;       const bool more = kt + 1 < nk;
;       if (more) G2_LOADR(kt + 1);
;       __builtin_amdgcn_sched_barrier(0);
;       gemm256_compute<TR>(acc, As0 + (kt & 1) * G2_STAGE, Bs0 + (kt & 1) * G2_STAGE);
;       __builtin_amdgcn_sched_barrier(0);
;       if (more) G2_STORER(lds + ((kt + 1) & 1) * G2_STAGE);
;       __syncthreads();
;     }
.LBB0_239:
	s_bitcmp1_b32 s5, 0
	s_cselect_b32 s32, 0x12000, 0
	v_add_u32_e32 v169, s32, v1
	v_add_u32_e32 v178, s32, v167
	ds_read_b128 v[170:173], v178 offset:36864
	ds_read_b128 v[180:183], v178 offset:41472
	ds_read_b128 v[174:177], v169 offset:4608
	ds_read_b128 v[184:187], v169 offset:9216
	ds_read_b128 v[188:191], v169 offset:13824
	ds_read_b128 v[192:195], v178 offset:36896
	s_waitcnt vmcnt(5)
	v_lshl_add_u64 v[138:139], v[164:165], 0, s[10:11]
	v_add_co_u32_e32 v130, vcc, s48, v138
	s_waitcnt vmcnt(1)
	v_lshl_add_u64 v[154:155], v[162:163], 0, s[10:11]
	v_addc_co_u32_e32 v131, vcc, 0, v139, vcc
	v_add_co_u32_e32 v134, vcc, s49, v138
	global_load_dwordx4 v[130:133], v[130:131], off
	s_nop 0
	v_addc_co_u32_e32 v135, vcc, 0, v139, vcc
	v_add_co_u32_e32 v140, vcc, s58, v138
	global_load_dwordx4 v[134:137], v[134:135], off
	s_nop 0
	v_addc_co_u32_e32 v141, vcc, 0, v139, vcc
	v_add_co_u32_e32 v142, vcc, s59, v138
	s_add_i32 s12, s5, 1
	s_nop 0
	v_addc_co_u32_e32 v143, vcc, 0, v139, vcc
	v_add_co_u32_e32 v146, vcc, s2, v154
	global_load_dwordx4 v[138:141], v[140:141], off
	s_nop 0
	v_addc_co_u32_e32 v147, vcc, 0, v155, vcc
	v_add_co_u32_e32 v150, vcc, s3, v154
	global_load_dwordx4 v[142:145], v[142:143], off
	s_nop 0
	v_addc_co_u32_e32 v151, vcc, 0, v155, vcc
	v_add_co_u32_e32 v156, vcc, s80, v154
	global_load_dwordx4 v[146:149], v[146:147], off
	s_nop 0
	v_addc_co_u32_e32 v157, vcc, 0, v155, vcc
	s_waitcnt vmcnt(5)
	v_add_co_u32_e32 v158, vcc, s81, v154
	global_load_dwordx4 v[150:153], v[150:151], off
	s_nop 0
	v_addc_co_u32_e32 v159, vcc, 0, v155, vcc
	global_load_dwordx4 v[154:157], v[156:157], off
	s_nop 0
	global_load_dwordx4 v[158:161], v[158:159], off
	s_bitcmp1_b32 s5, 0
	s_cselect_b32 s5, 0x12000, 0
	s_setprio 2
	s_waitcnt lgkmcnt(3)
	v_mfma_f32_32x32x16_bf16 v[34:49], v[170:173], v[174:177], v[34:49]
	v_mfma_f32_32x32x16_bf16 v[50:65], v[180:183], v[174:177], v[50:65]
	s_waitcnt lgkmcnt(2)
	v_mfma_f32_32x32x16_bf16 v[66:81], v[170:173], v[184:187], v[66:81]
	v_mfma_f32_32x32x16_bf16 v[82:97], v[180:183], v[184:187], v[82:97]
	s_waitcnt lgkmcnt(1)
	v_mfma_f32_32x32x16_bf16 v[98:113], v[170:173], v[188:191], v[98:113]
	v_mfma_f32_32x32x16_bf16 v[114:129], v[180:183], v[188:191], v[114:129]
	ds_read_b128 v[174:177], v178 offset:41504
	ds_read_b128 v[184:187], v169
	ds_read_b128 v[200:203], v169 offset:9248
	ds_read_b128 v[204:207], v169 offset:13856
	s_waitcnt lgkmcnt(2)
	v_mfma_f32_32x32x16_bf16 v[18:33], v[180:183], v[184:187], v[18:33]
	s_waitcnt lgkmcnt(1)
	v_mfma_f32_32x32x16_bf16 v[66:81], v[192:195], v[200:203], v[66:81]
	v_mfma_f32_32x32x16_bf16 v[82:97], v[174:177], v[200:203], v[82:97]
	ds_read_b128 v[180:183], v178 offset:41536
	ds_read_b128 v[200:203], v169 offset:13888
	s_waitcnt lgkmcnt(2)
	v_mfma_f32_32x32x16_bf16 v[114:129], v[174:177], v[204:207], v[114:129]
	s_waitcnt lgkmcnt(0)
	v_mfma_f32_32x32x16_bf16 v[114:129], v[180:183], v[200:203], v[114:129]
	v_mfma_f32_32x32x16_bf16 v[2:17], v[170:173], v[184:187], v[2:17]
	ds_read_b128 v[170:173], v178 offset:36928
	v_mfma_f32_32x32x16_bf16 v[98:113], v[192:195], v[204:207], v[98:113]
	s_waitcnt lgkmcnt(0)
	v_mfma_f32_32x32x16_bf16 v[98:113], v[170:173], v[200:203], v[98:113]
	ds_read_b128 v[188:191], v169 offset:32
	ds_read_b128 v[196:199], v169 offset:4640
	s_waitcnt lgkmcnt(1)
	v_mfma_f32_32x32x16_bf16 v[2:17], v[192:195], v[188:191], v[2:17]
	v_mfma_f32_32x32x16_bf16 v[18:33], v[174:177], v[188:191], v[18:33]
	s_waitcnt lgkmcnt(0)
	v_mfma_f32_32x32x16_bf16 v[34:49], v[192:195], v[196:199], v[34:49]
	v_mfma_f32_32x32x16_bf16 v[50:65], v[174:177], v[196:199], v[50:65]
	ds_read_b128 v[184:187], v169 offset:64
	ds_read_b128 v[188:191], v169 offset:4672
	ds_read_b128 v[196:199], v169 offset:9280
	ds_read_b128 v[174:177], v169 offset:96
	s_waitcnt lgkmcnt(3)
	v_mfma_f32_32x32x16_bf16 v[2:17], v[170:173], v[184:187], v[2:17]
	v_mfma_f32_32x32x16_bf16 v[18:33], v[180:183], v[184:187], v[18:33]
	s_waitcnt lgkmcnt(2)
	v_mfma_f32_32x32x16_bf16 v[34:49], v[170:173], v[188:191], v[34:49]
	v_mfma_f32_32x32x16_bf16 v[50:65], v[180:183], v[188:191], v[50:65]
	s_waitcnt lgkmcnt(1)
	v_mfma_f32_32x32x16_bf16 v[66:81], v[170:173], v[196:199], v[66:81]
	ds_read_b128 v[170:173], v178 offset:36960
	v_mfma_f32_32x32x16_bf16 v[82:97], v[180:183], v[196:199], v[82:97]
	ds_read_b128 v[180:183], v178 offset:41568
	s_waitcnt lgkmcnt(1)
	v_mfma_f32_32x32x16_bf16 v[2:17], v[170:173], v[174:177], v[2:17]
	s_waitcnt lgkmcnt(0)
	v_mfma_f32_32x32x16_bf16 v[18:33], v[180:183], v[174:177], v[18:33]
	ds_read_b128 v[174:177], v169 offset:4704
	s_waitcnt lgkmcnt(0)
	v_mfma_f32_32x32x16_bf16 v[34:49], v[170:173], v[174:177], v[34:49]
	v_mfma_f32_32x32x16_bf16 v[50:65], v[180:183], v[174:177], v[50:65]
	ds_read_b128 v[174:177], v169 offset:9312
	s_waitcnt lgkmcnt(0)
	v_mfma_f32_32x32x16_bf16 v[66:81], v[170:173], v[174:177], v[66:81]
	v_mfma_f32_32x32x16_bf16 v[82:97], v[180:183], v[174:177], v[82:97]
	ds_read_b128 v[174:177], v169 offset:13920
	s_waitcnt lgkmcnt(0)
	v_mfma_f32_32x32x16_bf16 v[98:113], v[170:173], v[174:177], v[98:113]
	v_mfma_f32_32x32x16_bf16 v[114:129], v[180:183], v[174:177], v[114:129]
	s_setprio 0
	s_bitcmp1_b32 s12, 0
	s_cselect_b32 s5, 0x12000, 0
	s_add_u32 s10, s10, 0x8000
	s_addc_u32 s11, s11, 0
	v_add_u32_e32 v169, s5, v168
	s_cmp_eq_u32 s10, 0x78000
	s_mov_b32 s5, s12
	s_waitcnt vmcnt(7)
	ds_write_b128 v169, v[130:133]
	s_waitcnt vmcnt(6)
	ds_write_b128 v169, v[134:137] offset:9216
	s_waitcnt vmcnt(5)
	ds_write_b128 v169, v[138:141] offset:18432
	s_waitcnt vmcnt(4)
	ds_write_b128 v169, v[142:145] offset:27648
	s_waitcnt vmcnt(3)
	ds_write_b128 v169, v[146:149] offset:36864
	s_waitcnt vmcnt(2)
	ds_write_b128 v169, v[150:153] offset:46080
	s_waitcnt vmcnt(1)
	ds_write_b128 v169, v[154:157] offset:55296
	s_waitcnt vmcnt(0)
	ds_write_b128 v169, v[158:161] offset:64512
	s_waitcnt lgkmcnt(0)
	s_barrier
; template <bool TR>
; DI void gemm256_compute(f32x16 (&acc)[4][2], const unsigned char* As, const unsigned char* Bs) {
;   __builtin_amdgcn_s_setprio(2);
;   bf16x8 b0 = *(const bf16x8*)(Bs), b1 = *(const bf16x8*)(Bs + 32 * G_AST);
;   bf16x8 a0 = *(const bf16x8*)(As), a1 = *(const bf16x8*)(As + 32 * G_AST), a2 = *(const bf16x8*)(As + 64 * G_AST), a3 = *(const bf16x8*)(As + 96 * G_AST);
; #pragma unroll
;   for (int ks = 0; ks < 4; ++ks) {
;     bf16x8 nb0 = b0, nb1 = b1, na0 = a0, na1 = a1, na2 = a2, na3 = a3;
;     if (ks < 3) {
;       nb0 = *(const bf16x8*)(Bs + (ks + 1) * 32); nb1 = *(const bf16x8*)(Bs + 32 * G_AST + (ks + 1) * 32);
;       na0 = *(const bf16x8*)(As + (ks + 1) * 32); na1 = *(const bf16x8*)(As + 32 * G_AST + (ks + 1) * 32);
;       na2 = *(const bf16x8*)(As + 64 * G_AST + (ks + 1) * 32); na3 = *(const bf16x8*)(As + 96 * G_AST + (ks + 1) * 32);
;     }
;     if (TR) {
;       acc[0][0] = MFMA16(b0, a0, acc[0][0]); acc[0][1] = MFMA16(b1, a0, acc[0][1]);
;       acc[1][0] = MFMA16(b0, a1, acc[1][0]); acc[1][1] = MFMA16(b1, a1, acc[1][1]);
;       acc[2][0] = MFMA16(b0, a2, acc[2][0]); acc[2][1] = MFMA16(b1, a2, acc[2][1]);
;       acc[3][0] = MFMA16(b0, a3, acc[3][0]); acc[3][1] = MFMA16(b1, a3, acc[3][1]);
;     } else {
;       acc[0][0] = MFMA16(a0, b0, acc[0][0]); acc[0][1] = MFMA16(a0, b1, acc[0][1]);
;       acc[1][0] = MFMA16(a1, b0, acc[1][0]); acc[1][1] = MFMA16(a1, b1, acc[1][1]);
;       acc[2][0] = MFMA16(a2, b0, acc[2][0]); acc[2][1] = MFMA16(a2, b1, acc[2][1]);
;       acc[3][0] = MFMA16(a3, b0, acc[3][0]); acc[3][1] = MFMA16(a3, b1, acc[3][1]);
;     }
;     if (ks < 3) {
;       __builtin_amdgcn_sched_group_barrier(0x100, 6, 0);
;       __builtin_amdgcn_sched_group_barrier(0x008, 8, 0);
;     }
;     b0 = nb0; b1 = nb1; a0 = na0; a1 = na1; a2 = na2; a3 = na3;
;   }
; template <bool TR = false>
; DI void gemm256(f32x16 (&acc)[4][2], const u16* const (&ap)[4], const u16* b0p, int K, unsigned char* lds) {
;     ...
;   if (!late) {
;     for (int kt = 0; kt < nk; ++kt) {
;       const bool more = kt + 1 < nk;
;       if (more) G2_LOADR(kt + 1);
;       __builtin_amdgcn_sched_barrier(0);
;       gemm256_compute<TR>(acc, As0 + (kt & 1) * G2_STAGE, Bs0 + (kt & 1) * G2_STAGE);
;       __builtin_amdgcn_sched_barrier(0);
;       if (more) G2_STORER(lds + ((kt + 1) & 1) * G2_STAGE);
;       __syncthreads();
;     }
	s_cbranch_scc0 .LBB0_239
	v_add_u32_e32 v138, 0x12000, v1
	v_add_u32_e32 v130, 0x12000, v166
	s_setprio 2
	v_add_u32_e32 v134, 0x13200, v166
	ds_read_b128 v[130:133], v130
	ds_read_b128 v[134:137], v134
	v_add_u32_e32 v142, 0x13200, v1
	v_add_u32_e32 v146, 0x14400, v1
	v_add_u32_e32 v150, 0x15600, v1
	ds_read_b128 v[138:141], v138
	ds_read_b128 v[142:145], v142
	ds_read_b128 v[146:149], v146
	ds_read_b128 v[150:153], v150
	s_waitcnt lgkmcnt(3)
	v_mfma_f32_32x32x16_bf16 v[2:17], v[130:133], v[138:141], v[2:17]
	v_mfma_f32_32x32x16_bf16 v[18:33], v[134:137], v[138:141], v[18:33]
	v_add_u32_e32 v138, 0x12020, v1
	s_waitcnt lgkmcnt(2)
	v_mfma_f32_32x32x16_bf16 v[34:49], v[130:133], v[142:145], v[34:49]
	v_mfma_f32_32x32x16_bf16 v[50:65], v[134:137], v[142:145], v[50:65]
	v_add_u32_e32 v142, 0x13220, v1
	s_waitcnt lgkmcnt(1)
	v_mfma_f32_32x32x16_bf16 v[66:81], v[130:133], v[146:149], v[66:81]
	v_mfma_f32_32x32x16_bf16 v[82:97], v[134:137], v[146:149], v[82:97]
	v_add_u32_e32 v146, 0x14420, v1
	s_waitcnt lgkmcnt(0)
	v_mfma_f32_32x32x16_bf16 v[98:113], v[130:133], v[150:153], v[98:113]
	v_add_u32_e32 v130, 0x12020, v166
	v_mfma_f32_32x32x16_bf16 v[114:129], v[134:137], v[150:153], v[114:129]
	v_add_u32_e32 v134, 0x13220, v166
	ds_read_b128 v[130:133], v130
	ds_read_b128 v[134:137], v134
	v_add_u32_e32 v150, 0x15620, v1
	ds_read_b128 v[138:141], v138
	ds_read_b128 v[142:145], v142
	ds_read_b128 v[146:149], v146
	ds_read_b128 v[150:153], v150
	s_waitcnt lgkmcnt(3)
	v_mfma_f32_32x32x16_bf16 v[2:17], v[130:133], v[138:141], v[2:17]
	v_mfma_f32_32x32x16_bf16 v[18:33], v[134:137], v[138:141], v[18:33]
	v_add_u32_e32 v138, 0x12040, v1
	s_waitcnt lgkmcnt(2)
	v_mfma_f32_32x32x16_bf16 v[34:49], v[130:133], v[142:145], v[34:49]
	v_mfma_f32_32x32x16_bf16 v[50:65], v[134:137], v[142:145], v[50:65]
	v_add_u32_e32 v142, 0x13240, v1
	s_waitcnt lgkmcnt(1)
	v_mfma_f32_32x32x16_bf16 v[66:81], v[130:133], v[146:149], v[66:81]
	v_mfma_f32_32x32x16_bf16 v[82:97], v[134:137], v[146:149], v[82:97]
	v_add_u32_e32 v146, 0x14440, v1
	s_waitcnt lgkmcnt(0)
	v_mfma_f32_32x32x16_bf16 v[98:113], v[130:133], v[150:153], v[98:113]
	v_add_u32_e32 v130, 0x12040, v166
	v_mfma_f32_32x32x16_bf16 v[114:129], v[134:137], v[150:153], v[114:129]
	v_add_u32_e32 v134, 0x13240, v166
	ds_read_b128 v[130:133], v130
	ds_read_b128 v[134:137], v134
	v_add_u32_e32 v150, 0x15640, v1
	ds_read_b128 v[138:141], v138
	ds_read_b128 v[142:145], v142
	ds_read_b128 v[146:149], v146
	ds_read_b128 v[150:153], v150
	s_waitcnt lgkmcnt(3)
	v_mfma_f32_32x32x16_bf16 v[2:17], v[130:133], v[138:141], v[2:17]
	v_mfma_f32_32x32x16_bf16 v[18:33], v[134:137], v[138:141], v[18:33]
	v_add_u32_e32 v138, 0x13260, v166
	ds_read_b128 v[138:141], v138
	s_waitcnt lgkmcnt(3)
	v_mfma_f32_32x32x16_bf16 v[34:49], v[130:133], v[142:145], v[34:49]
	s_waitcnt lgkmcnt(2)
	v_mfma_f32_32x32x16_bf16 v[66:81], v[130:133], v[146:149], v[66:81]
	s_waitcnt lgkmcnt(1)
	v_mfma_f32_32x32x16_bf16 v[98:113], v[130:133], v[150:153], v[98:113]
	v_add_u32_e32 v130, 0x12060, v166
	ds_read_b128 v[130:133], v130
	v_mfma_f32_32x32x16_bf16 v[50:65], v[134:137], v[142:145], v[50:65]
	v_mfma_f32_32x32x16_bf16 v[82:97], v[134:137], v[146:149], v[82:97]
	v_mfma_f32_32x32x16_bf16 v[114:129], v[134:137], v[150:153], v[114:129]
	v_add_u32_e32 v134, 0x12060, v1
	ds_read_b128 v[134:137], v134
	s_waitcnt lgkmcnt(0)
	v_mfma_f32_32x32x16_bf16 v[2:17], v[130:133], v[134:137], v[2:17]
	v_mfma_f32_32x32x16_bf16 v[18:33], v[138:141], v[134:137], v[18:33]
	v_add_u32_e32 v134, 0x13260, v1
	ds_read_b128 v[134:137], v134
	s_waitcnt lgkmcnt(0)
	v_mfma_f32_32x32x16_bf16 v[34:49], v[130:133], v[134:137], v[34:49]
	v_mfma_f32_32x32x16_bf16 v[50:65], v[138:141], v[134:137], v[50:65]
	v_add_u32_e32 v134, 0x14460, v1
	ds_read_b128 v[134:137], v134
	v_add_u32_e32 v1, 0x15660, v1
	s_waitcnt lgkmcnt(0)
	v_mfma_f32_32x32x16_bf16 v[66:81], v[130:133], v[134:137], v[66:81]
	v_mfma_f32_32x32x16_bf16 v[82:97], v[138:141], v[134:137], v[82:97]
	ds_read_b128 v[134:137], v1
	s_waitcnt lgkmcnt(0)
	v_mfma_f32_32x32x16_bf16 v[98:113], v[130:133], v[134:137], v[98:113]
	v_mfma_f32_32x32x16_bf16 v[114:129], v[138:141], v[134:137], v[114:129]
	s_setprio 0
	s_barrier

; template <bool TR>
; DI void gemm256_compute(f32x16 (&acc)[4][2], const unsigned char* As, const unsigned char* Bs) {
;   __builtin_amdgcn_s_setprio(2);
;   bf16x8 b0 = *(const bf16x8*)(Bs), b1 = *(const bf16x8*)(Bs + 32 * G_AST);
;   bf16x8 a0 = *(const bf16x8*)(As), a1 = *(const bf16x8*)(As + 32 * G_AST), a2 = *(const bf16x8*)(As + 64 * G_AST), a3 = *(const bf16x8*)(As + 96 * G_AST);
; #pragma unroll
;   for (int ks = 0; ks < 4; ++ks) {
;     bf16x8 nb0 = b0, nb1 = b1, na0 = a0, na1 = a1, na2 = a2, na3 = a3;
;     if (ks < 3) {
;       nb0 = *(const bf16x8*)(Bs + (ks + 1) * 32); nb1 = *(const bf16x8*)(Bs + 32 * G_AST + (ks + 1) * 32);
;       na0 = *(const bf16x8*)(As + (ks + 1) * 32); na1 = *(const bf16x8*)(As + 32 * G_AST + (ks + 1) * 32);
;       na2 = *(const bf16x8*)(As + 64 * G_AST + (ks + 1) * 32); na3 = *(const bf16x8*)(As + 96 * G_AST + (ks + 1) * 32);
;     }
;     if (TR) {
;       acc[0][0] = MFMA16(b0, a0, acc[0][0]); acc[0][1] = MFMA16(b1, a0, acc[0][1]);
;       acc[1][0] = MFMA16(b0, a1, acc[1][0]); acc[1][1] = MFMA16(b1, a1, acc[1][1]);
;       acc[2][0] = MFMA16(b0, a2, acc[2][0]); acc[2][1] = MFMA16(b1, a2, acc[2][1]);
;       acc[3][0] = MFMA16(b0, a3, acc[3][0]); acc[3][1] = MFMA16(b1, a3, acc[3][1]);
;     } else {
;       acc[0][0] = MFMA16(a0, b0, acc[0][0]); acc[0][1] = MFMA16(a0, b1, acc[0][1]);
;       acc[1][0] = MFMA16(a1, b0, acc[1][0]); acc[1][1] = MFMA16(a1, b1, acc[1][1]);
;       acc[2][0] = MFMA16(a2, b0, acc[2][0]); acc[2][1] = MFMA16(a2, b1, acc[2][1]);
;       acc[3][0] = MFMA16(a3, b0, acc[3][0]); acc[3][1] = MFMA16(a3, b1, acc[3][1]);
;     }
;     if (ks < 3) {
;       __builtin_amdgcn_sched_group_barrier(0x100, 6, 0);
;       __builtin_amdgcn_sched_group_barrier(0x008, 8, 0);
;     }
;     b0 = nb0; b1 = nb1; a0 = na0; a1 = na1; a2 = na2; a3 = na3;
;   }
; template <bool TR = false>
; DI void gemm256(f32x16 (&acc)[4][2], const u16* const (&ap)[4], const u16* b0p, int K, unsigned char* lds) {
;     ...
;   if (!late) {
;     for (int kt = 0; kt < nk; ++kt) {
;       const bool more = kt + 1 < nk;
;       if (more) G2_LOADR(kt + 1);
;       __builtin_amdgcn_sched_barrier(0);
;       gemm256_compute<TR>(acc, As0 + (kt & 1) * G2_STAGE, Bs0 + (kt & 1) * G2_STAGE);
;       __builtin_amdgcn_sched_barrier(0);
;       if (more) G2_STORER(lds + ((kt + 1) & 1) * G2_STAGE);
;       __syncthreads();
;     }
.LBB0_1424:
	s_bitcmp1_b32 s7, 0
	s_cselect_b32 s32, 0x12000, 0
	v_add_u32_e32 v178, s32, v171
	v_add_u32_e32 v192, s32, v175
	ds_read_b128 v[188:191], v178 offset:4608
	ds_read_b128 v[208:211], v178 offset:9216
	ds_read_b128 v[226:229], v178 offset:13824
	ds_read_b128 v[200:203], v192 offset:36864
	ds_read_b128 v[204:207], v192 offset:41472
	ds_read_b128 v[232:235], v192 offset:36896
	s_waitcnt vmcnt(1)
	v_lshl_add_u64 v[154:155], v[176:177], 0, s[8:9]
	s_mov_b32 s10, 0xf08000
	v_add_co_u32_e32 v146, vcc, s10, v154
	s_mov_b32 s10, 0xf0a000
	s_nop 0
	v_addc_co_u32_e32 v147, vcc, 0, v155, vcc
	v_add_co_u32_e32 v150, vcc, s10, v154
	s_mov_b32 s10, 0xf0c000
	s_nop 0
	v_addc_co_u32_e32 v151, vcc, 0, v155, vcc
	v_add_co_u32_e32 v156, vcc, s10, v154
	s_mov_b32 s10, 0xf0e000
	s_nop 0
	v_addc_co_u32_e32 v157, vcc, 0, v155, vcc
	s_waitcnt vmcnt(0)
	v_add_co_u32_e32 v158, vcc, s10, v154
	v_lshl_add_u64 v[130:131], v[180:181], 0, s[8:9]
	v_lshl_add_u64 v[134:135], v[182:183], 0, s[8:9]
	v_lshl_add_u64 v[138:139], v[184:185], 0, s[8:9]
	v_lshl_add_u64 v[142:143], v[186:187], 0, s[8:9]
	v_addc_co_u32_e32 v159, vcc, 0, v155, vcc
	global_load_dwordx4 v[130:133], v[130:131], off
	s_add_i32 s10, s7, 1
	global_load_dwordx4 v[134:137], v[134:135], off
	s_nop 0
	global_load_dwordx4 v[138:141], v[138:139], off
	s_nop 0
	global_load_dwordx4 v[142:145], v[142:143], off
	s_nop 0
	global_load_dwordx4 v[146:149], v[146:147], off
	s_nop 0
	global_load_dwordx4 v[150:153], v[150:151], off
	s_nop 0
	global_load_dwordx4 v[154:157], v[156:157], off
	s_nop 0
	global_load_dwordx4 v[158:161], v[158:159], off
	s_bitcmp1_b32 s7, 0
	s_cselect_b32 s7, 0x12000, 0
	s_setprio 2
	s_waitcnt lgkmcnt(2)
	v_mfma_f32_32x32x16_bf16 v[82:97], v[188:191], v[200:203], v[82:97]
	s_waitcnt lgkmcnt(1)
	v_mfma_f32_32x32x16_bf16 v[66:81], v[188:191], v[204:207], v[66:81]
	v_mfma_f32_32x32x16_bf16 v[50:65], v[208:211], v[200:203], v[50:65]
	v_mfma_f32_32x32x16_bf16 v[34:49], v[208:211], v[204:207], v[34:49]
	v_mfma_f32_32x32x16_bf16 v[18:33], v[226:229], v[200:203], v[18:33]
	v_mfma_f32_32x32x16_bf16 v[2:17], v[226:229], v[204:207], v[2:17]
	ds_read_b128 v[188:191], v178
	ds_read_b128 v[240:243], v178 offset:9248
	ds_read_b128 v[244:247], v178 offset:13856
	ds_read_b128 v[208:211], v192 offset:41504
	s_waitcnt lgkmcnt(3)
	v_mfma_f32_32x32x16_bf16 v[114:129], v[188:191], v[200:203], v[114:129]
	s_waitcnt lgkmcnt(2)
	v_mfma_f32_32x32x16_bf16 v[50:65], v[240:243], v[232:235], v[50:65]
	s_waitcnt lgkmcnt(0)
	v_mfma_f32_32x32x16_bf16 v[34:49], v[240:243], v[208:211], v[34:49]
	ds_read_b128 v[240:243], v178 offset:13888
	ds_read_b128 v[200:203], v192 offset:41536
	v_mfma_f32_32x32x16_bf16 v[2:17], v[244:247], v[208:211], v[2:17]
	s_waitcnt lgkmcnt(0)
	v_mfma_f32_32x32x16_bf16 v[2:17], v[240:243], v[200:203], v[2:17]
	v_mfma_f32_32x32x16_bf16 v[98:113], v[188:191], v[204:207], v[98:113]
	ds_read_b128 v[188:191], v192 offset:36928
	v_mfma_f32_32x32x16_bf16 v[18:33], v[244:247], v[232:235], v[18:33]
	s_waitcnt lgkmcnt(0)
	v_mfma_f32_32x32x16_bf16 v[18:33], v[240:243], v[188:191], v[18:33]
	ds_read_b128 v[226:229], v178 offset:32
	ds_read_b128 v[236:239], v178 offset:4640
	s_waitcnt lgkmcnt(1)
	v_mfma_f32_32x32x16_bf16 v[114:129], v[226:229], v[232:235], v[114:129]
	v_mfma_f32_32x32x16_bf16 v[98:113], v[226:229], v[208:211], v[98:113]
	s_waitcnt lgkmcnt(0)
	v_mfma_f32_32x32x16_bf16 v[82:97], v[236:239], v[232:235], v[82:97]
	v_mfma_f32_32x32x16_bf16 v[66:81], v[236:239], v[208:211], v[66:81]
	ds_read_b128 v[204:207], v178 offset:64
	ds_read_b128 v[226:229], v178 offset:4672
	ds_read_b128 v[236:239], v178 offset:9280
	s_waitcnt lgkmcnt(2)
	v_mfma_f32_32x32x16_bf16 v[114:129], v[204:207], v[188:191], v[114:129]
	s_waitcnt lgkmcnt(1)
	v_mfma_f32_32x32x16_bf16 v[82:97], v[226:229], v[188:191], v[82:97]
	s_waitcnt lgkmcnt(0)
	v_mfma_f32_32x32x16_bf16 v[50:65], v[236:239], v[188:191], v[50:65]
	ds_read_b128 v[188:191], v178 offset:96
	v_mfma_f32_32x32x16_bf16 v[98:113], v[204:207], v[200:203], v[98:113]
	ds_read_b128 v[204:207], v192 offset:41568
	v_mfma_f32_32x32x16_bf16 v[66:81], v[226:229], v[200:203], v[66:81]
	v_mfma_f32_32x32x16_bf16 v[34:49], v[236:239], v[200:203], v[34:49]
	ds_read_b128 v[200:203], v192 offset:36960
	s_waitcnt lgkmcnt(0)
	v_mfma_f32_32x32x16_bf16 v[114:129], v[188:191], v[200:203], v[114:129]
	v_mfma_f32_32x32x16_bf16 v[98:113], v[188:191], v[204:207], v[98:113]
	ds_read_b128 v[188:191], v178 offset:4704
	s_waitcnt lgkmcnt(0)
	v_mfma_f32_32x32x16_bf16 v[82:97], v[188:191], v[200:203], v[82:97]
	v_mfma_f32_32x32x16_bf16 v[66:81], v[188:191], v[204:207], v[66:81]
	ds_read_b128 v[188:191], v178 offset:9312
	s_waitcnt lgkmcnt(0)
	v_mfma_f32_32x32x16_bf16 v[50:65], v[188:191], v[200:203], v[50:65]
	v_mfma_f32_32x32x16_bf16 v[34:49], v[188:191], v[204:207], v[34:49]
	ds_read_b128 v[188:191], v178 offset:13920
	s_waitcnt lgkmcnt(0)
	v_mfma_f32_32x32x16_bf16 v[18:33], v[188:191], v[200:203], v[18:33]
	v_mfma_f32_32x32x16_bf16 v[2:17], v[188:191], v[204:207], v[2:17]
	s_setprio 0
	s_bitcmp1_b32 s10, 0
	s_cselect_b32 s7, 0x12000, 0
	s_add_u32 s8, s8, 0x8000
	s_addc_u32 s9, s9, 0
	v_add_u32_e32 v178, s7, v198
	s_cmp_eq_u32 s8, 0x78000
	s_mov_b32 s7, s10
	s_waitcnt vmcnt(7)
	ds_write_b128 v178, v[130:133]
	s_waitcnt vmcnt(6)
	ds_write_b128 v178, v[134:137] offset:9216
	s_waitcnt vmcnt(5)
	ds_write_b128 v178, v[138:141] offset:18432
	s_waitcnt vmcnt(4)
	ds_write_b128 v178, v[142:145] offset:27648
	s_waitcnt vmcnt(3)
	ds_write_b128 v178, v[146:149] offset:36864
	s_waitcnt vmcnt(2)
	ds_write_b128 v178, v[150:153] offset:46080
	s_waitcnt vmcnt(1)
	ds_write_b128 v178, v[154:157] offset:55296
	s_waitcnt vmcnt(0)
	ds_write_b128 v178, v[158:161] offset:64512
	s_waitcnt lgkmcnt(0)
	s_barrier
; template <bool TR>
; DI void gemm256_compute(f32x16 (&acc)[4][2], const unsigned char* As, const unsigned char* Bs) {
;   __builtin_amdgcn_s_setprio(2);
;   bf16x8 b0 = *(const bf16x8*)(Bs), b1 = *(const bf16x8*)(Bs + 32 * G_AST);
;   bf16x8 a0 = *(const bf16x8*)(As), a1 = *(const bf16x8*)(As + 32 * G_AST), a2 = *(const bf16x8*)(As + 64 * G_AST), a3 = *(const bf16x8*)(As + 96 * G_AST);
; #pragma unroll
;   for (int ks = 0; ks < 4; ++ks) {
;     bf16x8 nb0 = b0, nb1 = b1, na0 = a0, na1 = a1, na2 = a2, na3 = a3;
;     if (ks < 3) {
;       nb0 = *(const bf16x8*)(Bs + (ks + 1) * 32); nb1 = *(const bf16x8*)(Bs + 32 * G_AST + (ks + 1) * 32);
;       na0 = *(const bf16x8*)(As + (ks + 1) * 32); na1 = *(const bf16x8*)(As + 32 * G_AST + (ks + 1) * 32);
;       na2 = *(const bf16x8*)(As + 64 * G_AST + (ks + 1) * 32); na3 = *(const bf16x8*)(As + 96 * G_AST + (ks + 1) * 32);
;     }
;     if (TR) {
;       acc[0][0] = MFMA16(b0, a0, acc[0][0]); acc[0][1] = MFMA16(b1, a0, acc[0][1]);
;       acc[1][0] = MFMA16(b0, a1, acc[1][0]); acc[1][1] = MFMA16(b1, a1, acc[1][1]);
;       acc[2][0] = MFMA16(b0, a2, acc[2][0]); acc[2][1] = MFMA16(b1, a2, acc[2][1]);
;       acc[3][0] = MFMA16(b0, a3, acc[3][0]); acc[3][1] = MFMA16(b1, a3, acc[3][1]);
;     } else {
;       acc[0][0] = MFMA16(a0, b0, acc[0][0]); acc[0][1] = MFMA16(a0, b1, acc[0][1]);
;       acc[1][0] = MFMA16(a1, b0, acc[1][0]); acc[1][1] = MFMA16(a1, b1, acc[1][1]);
;       acc[2][0] = MFMA16(a2, b0, acc[2][0]); acc[2][1] = MFMA16(a2, b1, acc[2][1]);
;       acc[3][0] = MFMA16(a3, b0, acc[3][0]); acc[3][1] = MFMA16(a3, b1, acc[3][1]);
;     }
;     if (ks < 3) {
;       __builtin_amdgcn_sched_group_barrier(0x100, 6, 0);
;       __builtin_amdgcn_sched_group_barrier(0x008, 8, 0);
;     }
;     b0 = nb0; b1 = nb1; a0 = na0; a1 = na1; a2 = na2; a3 = na3;
;   }
; template <bool TR = false>
; DI void gemm256(f32x16 (&acc)[4][2], const u16* const (&ap)[4], const u16* b0p, int K, unsigned char* lds) {
;     ...
;   if (!late) {
;     for (int kt = 0; kt < nk; ++kt) {
;       const bool more = kt + 1 < nk;
;       if (more) G2_LOADR(kt + 1);
;       __builtin_amdgcn_sched_barrier(0);
;       gemm256_compute<TR>(acc, As0 + (kt & 1) * G2_STAGE, Bs0 + (kt & 1) * G2_STAGE);
;       __builtin_amdgcn_sched_barrier(0);
;       if (more) G2_STORER(lds + ((kt + 1) & 1) * G2_STAGE);
;       __syncthreads();
;     }
	s_cbranch_scc0 .LBB0_1424
	v_add_u32_e32 v134, 0x12000, v171
	v_add_u32_e32 v130, 0x12000, v173
	s_setprio 2
	v_add_u32_e32 v142, 0x13200, v171
	v_add_u32_e32 v146, 0x14400, v171
	v_add_u32_e32 v150, 0x15600, v171
	ds_read_b128 v[134:137], v134
	ds_read_b128 v[142:145], v142
	ds_read_b128 v[146:149], v146
	ds_read_b128 v[150:153], v150
	v_add_u32_e32 v138, 0x13200, v173
	ds_read_b128 v[130:133], v130
	ds_read_b128 v[138:141], v138
	s_waitcnt lgkmcnt(1)
	v_mfma_f32_32x32x16_bf16 v[114:129], v[134:137], v[130:133], v[114:129]
	s_waitcnt lgkmcnt(0)
	v_mfma_f32_32x32x16_bf16 v[98:113], v[134:137], v[138:141], v[98:113]
	v_add_u32_e32 v134, 0x12020, v171
	v_mfma_f32_32x32x16_bf16 v[82:97], v[142:145], v[130:133], v[82:97]
	v_mfma_f32_32x32x16_bf16 v[66:81], v[142:145], v[138:141], v[66:81]
	v_add_u32_e32 v142, 0x13220, v171
	v_mfma_f32_32x32x16_bf16 v[50:65], v[146:149], v[130:133], v[50:65]
	v_mfma_f32_32x32x16_bf16 v[34:49], v[146:149], v[138:141], v[34:49]
	v_add_u32_e32 v146, 0x14420, v171
	v_mfma_f32_32x32x16_bf16 v[18:33], v[150:153], v[130:133], v[18:33]
	v_add_u32_e32 v130, 0x12020, v173
	v_mfma_f32_32x32x16_bf16 v[2:17], v[150:153], v[138:141], v[2:17]
	v_add_u32_e32 v150, 0x15620, v171
	ds_read_b128 v[134:137], v134
	ds_read_b128 v[142:145], v142
	ds_read_b128 v[146:149], v146
	ds_read_b128 v[150:153], v150
	v_add_u32_e32 v138, 0x13220, v173
	ds_read_b128 v[130:133], v130
	ds_read_b128 v[138:141], v138
	s_waitcnt lgkmcnt(1)
	v_mfma_f32_32x32x16_bf16 v[114:129], v[134:137], v[130:133], v[114:129]
	s_waitcnt lgkmcnt(0)
	v_mfma_f32_32x32x16_bf16 v[98:113], v[134:137], v[138:141], v[98:113]
	v_add_u32_e32 v134, 0x12040, v171
	v_mfma_f32_32x32x16_bf16 v[82:97], v[142:145], v[130:133], v[82:97]
	v_mfma_f32_32x32x16_bf16 v[66:81], v[142:145], v[138:141], v[66:81]
	v_add_u32_e32 v142, 0x13240, v171
	v_mfma_f32_32x32x16_bf16 v[50:65], v[146:149], v[130:133], v[50:65]
	v_mfma_f32_32x32x16_bf16 v[34:49], v[146:149], v[138:141], v[34:49]
	v_add_u32_e32 v146, 0x14440, v171
	v_mfma_f32_32x32x16_bf16 v[18:33], v[150:153], v[130:133], v[18:33]
	v_add_u32_e32 v130, 0x12040, v173
	v_mfma_f32_32x32x16_bf16 v[2:17], v[150:153], v[138:141], v[2:17]
	v_add_u32_e32 v150, 0x15640, v171
	ds_read_b128 v[134:137], v134
	ds_read_b128 v[142:145], v142
	ds_read_b128 v[146:149], v146
	ds_read_b128 v[150:153], v150
	ds_read_b128 v[130:133], v130
	v_add_u32_e32 v138, 0x13240, v173
	ds_read_b128 v[138:141], v138
	s_waitcnt lgkmcnt(1)
	v_mfma_f32_32x32x16_bf16 v[114:129], v[134:137], v[130:133], v[114:129]
	v_mfma_f32_32x32x16_bf16 v[82:97], v[142:145], v[130:133], v[82:97]
	v_mfma_f32_32x32x16_bf16 v[50:65], v[146:149], v[130:133], v[50:65]
	v_mfma_f32_32x32x16_bf16 v[18:33], v[150:153], v[130:133], v[18:33]
	v_add_u32_e32 v130, 0x12060, v171
	ds_read_b128 v[130:133], v130
	s_waitcnt lgkmcnt(1)
	v_mfma_f32_32x32x16_bf16 v[98:113], v[134:137], v[138:141], v[98:113]
	v_add_u32_e32 v134, 0x12060, v173
	ds_read_b128 v[134:137], v134
	v_mfma_f32_32x32x16_bf16 v[66:81], v[142:145], v[138:141], v[66:81]
	v_add_u32_e32 v142, 0x13260, v171
	v_mfma_f32_32x32x16_bf16 v[34:49], v[146:149], v[138:141], v[34:49]
	v_mfma_f32_32x32x16_bf16 v[2:17], v[150:153], v[138:141], v[2:17]
	v_add_u32_e32 v138, 0x13260, v173
	ds_read_b128 v[138:141], v138
	s_waitcnt lgkmcnt(1)
	v_mfma_f32_32x32x16_bf16 v[114:129], v[130:133], v[134:137], v[114:129]
	s_waitcnt lgkmcnt(0)
	v_mfma_f32_32x32x16_bf16 v[98:113], v[130:133], v[138:141], v[98:113]
	ds_read_b128 v[130:133], v142
	v_add_u32_e32 v142, 0x14460, v171
	s_waitcnt lgkmcnt(0)
	v_mfma_f32_32x32x16_bf16 v[82:97], v[130:133], v[134:137], v[82:97]
	v_mfma_f32_32x32x16_bf16 v[66:81], v[130:133], v[138:141], v[66:81]
	ds_read_b128 v[130:133], v142
	v_add_u32_e32 v142, 0x15660, v171
	s_waitcnt lgkmcnt(0)
	v_mfma_f32_32x32x16_bf16 v[50:65], v[130:133], v[134:137], v[50:65]
	v_mfma_f32_32x32x16_bf16 v[34:49], v[130:133], v[138:141], v[34:49]
	ds_read_b128 v[130:133], v142
	s_waitcnt lgkmcnt(0)
	v_mfma_f32_32x32x16_bf16 v[18:33], v[130:133], v[134:137], v[18:33]
	v_mfma_f32_32x32x16_bf16 v[2:17], v[130:133], v[138:141], v[2:17]
	s_setprio 0
	s_barrier

; template <bool TR>
; DI void gemm256_compute(f32x16 (&acc)[4][2], const unsigned char* As, const unsigned char* Bs) {
;   __builtin_amdgcn_s_setprio(2);
;   bf16x8 b0 = *(const bf16x8*)(Bs), b1 = *(const bf16x8*)(Bs + 32 * G_AST);
;   bf16x8 a0 = *(const bf16x8*)(As), a1 = *(const bf16x8*)(As + 32 * G_AST), a2 = *(const bf16x8*)(As + 64 * G_AST), a3 = *(const bf16x8*)(As + 96 * G_AST);
; #pragma unroll
;   for (int ks = 0; ks < 4; ++ks) {
;     bf16x8 nb0 = b0, nb1 = b1, na0 = a0, na1 = a1, na2 = a2, na3 = a3;
;     if (ks < 3) {
;       nb0 = *(const bf16x8*)(Bs + (ks + 1) * 32); nb1 = *(const bf16x8*)(Bs + 32 * G_AST + (ks + 1) * 32);
;       na0 = *(const bf16x8*)(As + (ks + 1) * 32); na1 = *(const bf16x8*)(As + 32 * G_AST + (ks + 1) * 32);
;       na2 = *(const bf16x8*)(As + 64 * G_AST + (ks + 1) * 32); na3 = *(const bf16x8*)(As + 96 * G_AST + (ks + 1) * 32);
;     }
;     if (TR) {
;       acc[0][0] = MFMA16(b0, a0, acc[0][0]); acc[0][1] = MFMA16(b1, a0, acc[0][1]);
;       acc[1][0] = MFMA16(b0, a1, acc[1][0]); acc[1][1] = MFMA16(b1, a1, acc[1][1]);
;       acc[2][0] = MFMA16(b0, a2, acc[2][0]); acc[2][1] = MFMA16(b1, a2, acc[2][1]);
;       acc[3][0] = MFMA16(b0, a3, acc[3][0]); acc[3][1] = MFMA16(b1, a3, acc[3][1]);
;     } else {
;       acc[0][0] = MFMA16(a0, b0, acc[0][0]); acc[0][1] = MFMA16(a0, b1, acc[0][1]);
;       acc[1][0] = MFMA16(a1, b0, acc[1][0]); acc[1][1] = MFMA16(a1, b1, acc[1][1]);
;       acc[2][0] = MFMA16(a2, b0, acc[2][0]); acc[2][1] = MFMA16(a2, b1, acc[2][1]);
;       acc[3][0] = MFMA16(a3, b0, acc[3][0]); acc[3][1] = MFMA16(a3, b1, acc[3][1]);
;     }
;     if (ks < 3) {
;       __builtin_amdgcn_sched_group_barrier(0x100, 6, 0);
;       __builtin_amdgcn_sched_group_barrier(0x008, 8, 0);
;     }
;     b0 = nb0; b1 = nb1; a0 = na0; a1 = na1; a2 = na2; a3 = na3;
;   }
; template <bool TR = false>
; DI void gemm256(f32x16 (&acc)[4][2], const u16* const (&ap)[4], const u16* b0p, int K, unsigned char* lds) {
;     ...
;   if (!late) {
;     for (int kt = 0; kt < nk; ++kt) {
;       const bool more = kt + 1 < nk;
;       if (more) G2_LOADR(kt + 1);
;       __builtin_amdgcn_sched_barrier(0);
;       gemm256_compute<TR>(acc, As0 + (kt & 1) * G2_STAGE, Bs0 + (kt & 1) * G2_STAGE);
;       __builtin_amdgcn_sched_barrier(0);
;       if (more) G2_STORER(lds + ((kt + 1) & 1) * G2_STAGE);
;       __syncthreads();
;     }
.LBB0_1485:
	s_bitcmp1_b32 s7, 0
	s_cselect_b32 s32, 0x12000, 0
	v_add_u32_e32 v236, s32, v171
	v_add_u32_e32 v237, s32, v182
	ds_read_b128 v[184:187], v236 offset:4608
	ds_read_b128 v[196:199], v236 offset:9216
	ds_read_b128 v[200:203], v236 offset:13824
	ds_read_b128 v[188:191], v237 offset:36864
	ds_read_b128 v[192:195], v237 offset:41472
	ds_read_b128 v[204:207], v237 offset:36896
	s_waitcnt vmcnt(5)
	v_lshl_add_u64 v[138:139], v[174:175], 0, s[10:11]
	s_mov_b32 s9, 0x2e954000
	v_add_co_u32_e32 v130, vcc, s9, v138
	s_mov_b32 s9, 0x2e956000
	s_nop 0
	v_addc_co_u32_e32 v131, vcc, 0, v139, vcc
	v_add_co_u32_e32 v134, vcc, s9, v138
	s_mov_b32 s9, 0x2e958000
	s_nop 0
	v_addc_co_u32_e32 v135, vcc, 0, v139, vcc
	v_add_co_u32_e32 v140, vcc, s9, v138
	s_mov_b32 s9, 0x2e95a000
	s_nop 0
	v_addc_co_u32_e32 v141, vcc, 0, v139, vcc
	s_waitcnt vmcnt(3)
	v_add_co_u32_e32 v142, vcc, s9, v138
	s_waitcnt vmcnt(1)
	v_lshl_add_u64 v[154:155], v[176:177], 0, s[10:11]
	v_addc_co_u32_e32 v143, vcc, 0, v139, vcc
	s_mov_b32 s9, 0x8f08000
	v_add_co_u32_e32 v146, vcc, s9, v154
	s_mov_b32 s9, 0x8f0a000
	s_nop 0
	v_addc_co_u32_e32 v147, vcc, 0, v155, vcc
	v_add_co_u32_e32 v150, vcc, s9, v154
	s_mov_b32 s9, 0x8f0c000
	s_nop 0
	v_addc_co_u32_e32 v151, vcc, 0, v155, vcc
	v_add_co_u32_e32 v156, vcc, s9, v154
	s_mov_b32 s9, 0x8f0e000
	s_nop 0
	v_addc_co_u32_e32 v157, vcc, 0, v155, vcc
	s_waitcnt vmcnt(0)
	v_add_co_u32_e32 v158, vcc, s9, v154
	global_load_dwordx4 v[130:133], v[130:131], off
	s_nop 0
	v_addc_co_u32_e32 v159, vcc, 0, v155, vcc
	global_load_dwordx4 v[134:137], v[134:135], off
	s_add_i32 s9, s7, 1
	global_load_dwordx4 v[138:141], v[140:141], off
	s_nop 0
	global_load_dwordx4 v[142:145], v[142:143], off
	s_nop 0
	global_load_dwordx4 v[146:149], v[146:147], off
	s_nop 0
	global_load_dwordx4 v[150:153], v[150:151], off
	s_nop 0
	global_load_dwordx4 v[154:157], v[156:157], off
	s_nop 0
	global_load_dwordx4 v[158:161], v[158:159], off
	s_bitcmp1_b32 s7, 0
	s_cselect_b32 s7, 0x12000, 0
	s_setprio 2
	s_waitcnt lgkmcnt(2)
	v_mfma_f32_32x32x16_bf16 v[98:113], v[184:187], v[188:191], v[98:113]
	s_waitcnt lgkmcnt(1)
	v_mfma_f32_32x32x16_bf16 v[34:49], v[184:187], v[192:195], v[34:49]
	v_mfma_f32_32x32x16_bf16 v[82:97], v[196:199], v[188:191], v[82:97]
	v_mfma_f32_32x32x16_bf16 v[18:33], v[196:199], v[192:195], v[18:33]
	v_mfma_f32_32x32x16_bf16 v[66:81], v[200:203], v[188:191], v[66:81]
	v_mfma_f32_32x32x16_bf16 v[2:17], v[200:203], v[192:195], v[2:17]
	ds_read_b128 v[184:187], v236
	ds_read_b128 v[226:229], v236 offset:9248
	ds_read_b128 v[232:235], v236 offset:13856
	ds_read_b128 v[196:199], v237 offset:41504
	s_waitcnt lgkmcnt(3)
	v_mfma_f32_32x32x16_bf16 v[114:129], v[184:187], v[188:191], v[114:129]
	s_waitcnt lgkmcnt(2)
	v_mfma_f32_32x32x16_bf16 v[82:97], v[226:229], v[204:207], v[82:97]
	s_waitcnt lgkmcnt(0)
	v_mfma_f32_32x32x16_bf16 v[18:33], v[226:229], v[196:199], v[18:33]
	ds_read_b128 v[226:229], v236 offset:13888
	ds_read_b128 v[188:191], v237 offset:41536
	v_mfma_f32_32x32x16_bf16 v[2:17], v[232:235], v[196:199], v[2:17]
	s_waitcnt lgkmcnt(0)
	v_mfma_f32_32x32x16_bf16 v[2:17], v[226:229], v[188:191], v[2:17]
	v_mfma_f32_32x32x16_bf16 v[50:65], v[184:187], v[192:195], v[50:65]
	ds_read_b128 v[184:187], v237 offset:36928
	v_mfma_f32_32x32x16_bf16 v[66:81], v[232:235], v[204:207], v[66:81]
	s_waitcnt lgkmcnt(0)
	v_mfma_f32_32x32x16_bf16 v[66:81], v[226:229], v[184:187], v[66:81]
	ds_read_b128 v[200:203], v236 offset:32
	ds_read_b128 v[208:211], v236 offset:4640
	s_waitcnt lgkmcnt(1)
	v_mfma_f32_32x32x16_bf16 v[114:129], v[200:203], v[204:207], v[114:129]
	v_mfma_f32_32x32x16_bf16 v[50:65], v[200:203], v[196:199], v[50:65]
	s_waitcnt lgkmcnt(0)
	v_mfma_f32_32x32x16_bf16 v[98:113], v[208:211], v[204:207], v[98:113]
	v_mfma_f32_32x32x16_bf16 v[34:49], v[208:211], v[196:199], v[34:49]
	ds_read_b128 v[192:195], v236 offset:64
	ds_read_b128 v[200:203], v236 offset:4672
	ds_read_b128 v[208:211], v236 offset:9280
	s_waitcnt lgkmcnt(2)
	v_mfma_f32_32x32x16_bf16 v[114:129], v[192:195], v[184:187], v[114:129]
	s_waitcnt lgkmcnt(1)
	v_mfma_f32_32x32x16_bf16 v[98:113], v[200:203], v[184:187], v[98:113]
	s_waitcnt lgkmcnt(0)
	v_mfma_f32_32x32x16_bf16 v[82:97], v[208:211], v[184:187], v[82:97]
	ds_read_b128 v[184:187], v236 offset:96
	v_mfma_f32_32x32x16_bf16 v[50:65], v[192:195], v[188:191], v[50:65]
	ds_read_b128 v[192:195], v237 offset:41568
	v_mfma_f32_32x32x16_bf16 v[34:49], v[200:203], v[188:191], v[34:49]
	v_mfma_f32_32x32x16_bf16 v[18:33], v[208:211], v[188:191], v[18:33]
	ds_read_b128 v[188:191], v237 offset:36960
	s_waitcnt lgkmcnt(0)
	v_mfma_f32_32x32x16_bf16 v[114:129], v[184:187], v[188:191], v[114:129]
	v_mfma_f32_32x32x16_bf16 v[50:65], v[184:187], v[192:195], v[50:65]
	ds_read_b128 v[184:187], v236 offset:4704
	s_waitcnt lgkmcnt(0)
	v_mfma_f32_32x32x16_bf16 v[98:113], v[184:187], v[188:191], v[98:113]
	v_mfma_f32_32x32x16_bf16 v[34:49], v[184:187], v[192:195], v[34:49]
	ds_read_b128 v[184:187], v236 offset:9312
	s_waitcnt lgkmcnt(0)
	v_mfma_f32_32x32x16_bf16 v[82:97], v[184:187], v[188:191], v[82:97]
	v_mfma_f32_32x32x16_bf16 v[18:33], v[184:187], v[192:195], v[18:33]
	ds_read_b128 v[184:187], v236 offset:13920
	s_waitcnt lgkmcnt(0)
	v_mfma_f32_32x32x16_bf16 v[66:81], v[184:187], v[188:191], v[66:81]
	v_mfma_f32_32x32x16_bf16 v[2:17], v[184:187], v[192:195], v[2:17]
	s_setprio 0
	s_bitcmp1_b32 s9, 0
	s_cselect_b32 s7, 0x12000, 0
	s_add_u32 s10, s10, 0x8000
	s_addc_u32 s11, s11, 0
	v_add_u32_e32 v184, s7, v183
	s_cmp_eq_u32 s10, 0x78000
	s_mov_b32 s7, s9
	s_waitcnt vmcnt(7)
	ds_write_b128 v184, v[130:133]
	s_waitcnt vmcnt(6)
	ds_write_b128 v184, v[134:137] offset:9216
	s_waitcnt vmcnt(5)
	ds_write_b128 v184, v[138:141] offset:18432
	s_waitcnt vmcnt(4)
	ds_write_b128 v184, v[142:145] offset:27648
	s_waitcnt vmcnt(3)
	ds_write_b128 v184, v[146:149] offset:36864
	s_waitcnt vmcnt(2)
	ds_write_b128 v184, v[150:153] offset:46080
	s_waitcnt vmcnt(1)
	ds_write_b128 v184, v[154:157] offset:55296
	s_waitcnt vmcnt(0)
	ds_write_b128 v184, v[158:161] offset:64512
	s_waitcnt lgkmcnt(0)
	s_barrier
; template <bool TR>
; DI void gemm256_compute(f32x16 (&acc)[4][2], const unsigned char* As, const unsigned char* Bs) {
;   __builtin_amdgcn_s_setprio(2);
;   bf16x8 b0 = *(const bf16x8*)(Bs), b1 = *(const bf16x8*)(Bs + 32 * G_AST);
;   bf16x8 a0 = *(const bf16x8*)(As), a1 = *(const bf16x8*)(As + 32 * G_AST), a2 = *(const bf16x8*)(As + 64 * G_AST), a3 = *(const bf16x8*)(As + 96 * G_AST);
; #pragma unroll
;   for (int ks = 0; ks < 4; ++ks) {
;     bf16x8 nb0 = b0, nb1 = b1, na0 = a0, na1 = a1, na2 = a2, na3 = a3;
;     if (ks < 3) {
;       nb0 = *(const bf16x8*)(Bs + (ks + 1) * 32); nb1 = *(const bf16x8*)(Bs + 32 * G_AST + (ks + 1) * 32);
;       na0 = *(const bf16x8*)(As + (ks + 1) * 32); na1 = *(const bf16x8*)(As + 32 * G_AST + (ks + 1) * 32);
;       na2 = *(const bf16x8*)(As + 64 * G_AST + (ks + 1) * 32); na3 = *(const bf16x8*)(As + 96 * G_AST + (ks + 1) * 32);
;     }
;     if (TR) {
;       acc[0][0] = MFMA16(b0, a0, acc[0][0]); acc[0][1] = MFMA16(b1, a0, acc[0][1]);
;       acc[1][0] = MFMA16(b0, a1, acc[1][0]); acc[1][1] = MFMA16(b1, a1, acc[1][1]);
;       acc[2][0] = MFMA16(b0, a2, acc[2][0]); acc[2][1] = MFMA16(b1, a2, acc[2][1]);
;       acc[3][0] = MFMA16(b0, a3, acc[3][0]); acc[3][1] = MFMA16(b1, a3, acc[3][1]);
;     } else {
;       acc[0][0] = MFMA16(a0, b0, acc[0][0]); acc[0][1] = MFMA16(a0, b1, acc[0][1]);
;       acc[1][0] = MFMA16(a1, b0, acc[1][0]); acc[1][1] = MFMA16(a1, b1, acc[1][1]);
;       acc[2][0] = MFMA16(a2, b0, acc[2][0]); acc[2][1] = MFMA16(a2, b1, acc[2][1]);
;       acc[3][0] = MFMA16(a3, b0, acc[3][0]); acc[3][1] = MFMA16(a3, b1, acc[3][1]);
;     }
;     if (ks < 3) {
;       __builtin_amdgcn_sched_group_barrier(0x100, 6, 0);
;       __builtin_amdgcn_sched_group_barrier(0x008, 8, 0);
;     }
;     b0 = nb0; b1 = nb1; a0 = na0; a1 = na1; a2 = na2; a3 = na3;
;   }
; template <bool TR = false>
; DI void gemm256(f32x16 (&acc)[4][2], const u16* const (&ap)[4], const u16* b0p, int K, unsigned char* lds) {
;     ...
;   if (!late) {
;     for (int kt = 0; kt < nk; ++kt) {
;       const bool more = kt + 1 < nk;
;       if (more) G2_LOADR(kt + 1);
;       __builtin_amdgcn_sched_barrier(0);
;       gemm256_compute<TR>(acc, As0 + (kt & 1) * G2_STAGE, Bs0 + (kt & 1) * G2_STAGE);
;       __builtin_amdgcn_sched_barrier(0);
;       if (more) G2_STORER(lds + ((kt + 1) & 1) * G2_STAGE);
;       __syncthreads();
;     }
	s_cbranch_scc0 .LBB0_1485
	v_add_u32_e32 v134, 0x12000, v171
	v_add_u32_e32 v130, 0x12000, v173
	s_setprio 2
	v_add_u32_e32 v142, 0x13200, v171
	v_add_u32_e32 v146, 0x14400, v171
	v_add_u32_e32 v150, 0x15600, v171
	ds_read_b128 v[134:137], v134
	ds_read_b128 v[142:145], v142
	ds_read_b128 v[146:149], v146
	ds_read_b128 v[150:153], v150
	v_add_u32_e32 v138, 0x13200, v173
	ds_read_b128 v[130:133], v130
	ds_read_b128 v[138:141], v138
	s_waitcnt lgkmcnt(1)
	v_mfma_f32_32x32x16_bf16 v[114:129], v[134:137], v[130:133], v[114:129]
	s_waitcnt lgkmcnt(0)
	v_mfma_f32_32x32x16_bf16 v[50:65], v[134:137], v[138:141], v[50:65]
	v_add_u32_e32 v134, 0x12020, v171
	v_mfma_f32_32x32x16_bf16 v[98:113], v[142:145], v[130:133], v[98:113]
	v_mfma_f32_32x32x16_bf16 v[34:49], v[142:145], v[138:141], v[34:49]
	v_add_u32_e32 v142, 0x13220, v171
	v_mfma_f32_32x32x16_bf16 v[82:97], v[146:149], v[130:133], v[82:97]
	v_mfma_f32_32x32x16_bf16 v[18:33], v[146:149], v[138:141], v[18:33]
	v_add_u32_e32 v146, 0x14420, v171
	v_mfma_f32_32x32x16_bf16 v[66:81], v[150:153], v[130:133], v[66:81]
	v_add_u32_e32 v130, 0x12020, v173
	v_mfma_f32_32x32x16_bf16 v[2:17], v[150:153], v[138:141], v[2:17]
	v_add_u32_e32 v150, 0x15620, v171
	ds_read_b128 v[134:137], v134
	ds_read_b128 v[142:145], v142
	ds_read_b128 v[146:149], v146
	ds_read_b128 v[150:153], v150
	v_add_u32_e32 v138, 0x13220, v173
	ds_read_b128 v[130:133], v130
	ds_read_b128 v[138:141], v138
	s_waitcnt lgkmcnt(1)
	v_mfma_f32_32x32x16_bf16 v[114:129], v[134:137], v[130:133], v[114:129]
	s_waitcnt lgkmcnt(0)
	v_mfma_f32_32x32x16_bf16 v[50:65], v[134:137], v[138:141], v[50:65]
	v_add_u32_e32 v134, 0x12040, v171
	v_mfma_f32_32x32x16_bf16 v[98:113], v[142:145], v[130:133], v[98:113]
	v_mfma_f32_32x32x16_bf16 v[34:49], v[142:145], v[138:141], v[34:49]
	v_add_u32_e32 v142, 0x13240, v171
	v_mfma_f32_32x32x16_bf16 v[82:97], v[146:149], v[130:133], v[82:97]
	v_mfma_f32_32x32x16_bf16 v[18:33], v[146:149], v[138:141], v[18:33]
	v_add_u32_e32 v146, 0x14440, v171
	v_mfma_f32_32x32x16_bf16 v[66:81], v[150:153], v[130:133], v[66:81]
	v_add_u32_e32 v130, 0x12040, v173
	v_mfma_f32_32x32x16_bf16 v[2:17], v[150:153], v[138:141], v[2:17]
	v_add_u32_e32 v150, 0x15640, v171
	ds_read_b128 v[134:137], v134
	ds_read_b128 v[142:145], v142
	ds_read_b128 v[146:149], v146
	ds_read_b128 v[150:153], v150
	ds_read_b128 v[130:133], v130
	v_add_u32_e32 v138, 0x13240, v173
	ds_read_b128 v[138:141], v138
	s_waitcnt lgkmcnt(1)
	v_mfma_f32_32x32x16_bf16 v[114:129], v[134:137], v[130:133], v[114:129]
	v_mfma_f32_32x32x16_bf16 v[98:113], v[142:145], v[130:133], v[98:113]
	v_mfma_f32_32x32x16_bf16 v[82:97], v[146:149], v[130:133], v[82:97]
	v_mfma_f32_32x32x16_bf16 v[66:81], v[150:153], v[130:133], v[66:81]
	v_add_u32_e32 v130, 0x12060, v171
	ds_read_b128 v[130:133], v130
	s_waitcnt lgkmcnt(1)
	v_mfma_f32_32x32x16_bf16 v[50:65], v[134:137], v[138:141], v[50:65]
	v_add_u32_e32 v134, 0x12060, v173
	ds_read_b128 v[134:137], v134
	v_mfma_f32_32x32x16_bf16 v[34:49], v[142:145], v[138:141], v[34:49]
	v_add_u32_e32 v142, 0x13260, v171
	v_mfma_f32_32x32x16_bf16 v[18:33], v[146:149], v[138:141], v[18:33]
	v_mfma_f32_32x32x16_bf16 v[2:17], v[150:153], v[138:141], v[2:17]
	v_add_u32_e32 v138, 0x13260, v173
	ds_read_b128 v[138:141], v138
	s_waitcnt lgkmcnt(1)
	v_mfma_f32_32x32x16_bf16 v[114:129], v[130:133], v[134:137], v[114:129]
	s_waitcnt lgkmcnt(0)
	v_mfma_f32_32x32x16_bf16 v[50:65], v[130:133], v[138:141], v[50:65]
	ds_read_b128 v[130:133], v142
	v_add_u32_e32 v142, 0x14460, v171
	s_waitcnt lgkmcnt(0)
	v_mfma_f32_32x32x16_bf16 v[98:113], v[130:133], v[134:137], v[98:113]
	v_mfma_f32_32x32x16_bf16 v[34:49], v[130:133], v[138:141], v[34:49]
	ds_read_b128 v[130:133], v142
	v_add_u32_e32 v142, 0x15660, v171
	s_waitcnt lgkmcnt(0)
	v_mfma_f32_32x32x16_bf16 v[82:97], v[130:133], v[134:137], v[82:97]
	v_mfma_f32_32x32x16_bf16 v[18:33], v[130:133], v[138:141], v[18:33]
	ds_read_b128 v[130:133], v142
	s_waitcnt lgkmcnt(0)
	v_mfma_f32_32x32x16_bf16 v[66:81], v[130:133], v[134:137], v[66:81]
	v_mfma_f32_32x32x16_bf16 v[2:17], v[130:133], v[138:141], v[2:17]
	s_setprio 0
	s_barrier
